# NA flash64 loop: skip cross-lane row-max reduction when no lane local max exceeds rescale threshold (bit-identical results)
# speedup vs baseline: 1.0107x; 1.0012x over previous
.LBB0_271:
	v_max_f32_e32 v0, v109, v109
	v_max_f32_e32 v2, v108, v108
	v_max_f32_e32 v0, v2, v0
	v_max3_f32 v0, v0, v110, v111
	v_max3_f32 v0, v0, v112, v113
	v_max3_f32 v0, v0, v114, v115
	v_max3_f32 v0, v0, v120, v121
	v_max3_f32 v0, v0, v122, v123
	v_max3_f32 v0, v0, v116, v117
	v_max3_f32 v0, v0, v118, v119
	s_xor_b64 s[82:83], s[8:9], -1
	s_and_b64 vcc, exec, s[8:9]
	s_cbranch_vccnz .Lna_full0
	s_mov_b32 s2, 0x41000000
	v_cmp_lt_f32_e32 vcc, s2, v0
	s_cbranch_vccz .LBB0_278
.Lna_full0:
	v_mov_b32_e32 v2, v0
	s_nop 1
	v_permlane32_swap_b32_e32 v0, v2
	v_max_f32_e32 v2, v2, v2
	v_max_f32_e32 v0, v0, v0
	v_max_f32_e32 v0, v0, v2
	v_mov_b32_e32 v2, v0
	s_nop 1
	v_permlane16_swap_b32_e32 v0, v2
	v_max_f32_e32 v2, v2, v2
	v_max_f32_e32 v0, v0, v0
	s_xor_b64 s[82:83], s[8:9], -1
	v_max_f32_e32 v0, v0, v2
	s_mov_b64 s[10:11], -1
	s_and_saveexec_b64 s[12:13], s[82:83]
	s_cbranch_execz .LBB0_276
	s_mov_b32 s2, 0x41000000
	v_cmp_lt_f32_e32 vcc, s2, v0
	s_cbranch_vccz .LBB0_274
	v_max_f32_e32 v0, v0, v0
	v_max_f32_e32 v0, 0, v0
	s_branch .LBB0_275

.LBB0_278:
	s_or_b64 exec, exec, vcc
	v_max_f32_e32 v0, v69, v69
	v_max_f32_e32 v2, v68, v68
	v_max_f32_e32 v0, v2, v0
	v_max3_f32 v0, v0, v70, v71
	v_max3_f32 v0, v0, v72, v73
	v_max3_f32 v0, v0, v74, v75
	v_max3_f32 v0, v0, v64, v65
	v_max3_f32 v0, v0, v66, v67
	v_max3_f32 v0, v0, v60, v61
	v_max3_f32 v0, v0, v62, v63
	s_and_b64 vcc, exec, s[8:9]
	s_cbranch_vccnz .Lna_full1
	s_mov_b32 s2, 0x41000000
	v_cmp_lt_f32_e32 vcc, s2, v0
	s_cbranch_vccz .LBB0_285
.Lna_full1:
	v_mov_b32_e32 v2, v0
	s_nop 1
	v_permlane32_swap_b32_e32 v0, v2
	v_max_f32_e32 v2, v2, v2
	v_max_f32_e32 v0, v0, v0
	v_max_f32_e32 v0, v0, v2
	v_mov_b32_e32 v2, v0
	s_nop 1
	v_permlane16_swap_b32_e32 v0, v2
	v_max_f32_e32 v2, v2, v2
	v_max_f32_e32 v0, v0, v0
	v_max_f32_e32 v0, v0, v2
	s_mov_b64 s[10:11], -1
	s_and_saveexec_b64 s[12:13], s[82:83]
	s_cbranch_execz .LBB0_283
	s_mov_b32 s2, 0x41000000
	v_cmp_lt_f32_e32 vcc, s2, v0
	s_cbranch_vccz .LBB0_281
	v_max_f32_e32 v0, v0, v0
	v_max_f32_e32 v0, 0, v0
	s_branch .LBB0_282
